# non-temporal hint on the final RMSNorm phase's f32 output stores (never re-read)
# speedup vs baseline: 1.0009x; 1.0009x over previous
; __device__ __forceinline__ float bf_lo(unsigned u) { return __uint_as_float(u << 16); }
; __device__ __forceinline__ float bf_hi(unsigned u) { return __uint_as_float(u & 0xffff0000u); }
; __device__ __forceinline__ void final_rows(const bf16_t* hb, const float* g, float* outf, int gw, int NGW, int lane, int m_lo, int m_hi) {
;     ...
;     for (int m0 = m_lo + gw; m0 < m_hi; m0 += 4 * NGW) {
;         u32x2 w[4][4];
; #pragma unroll
;         for (int r = 0; r < 4; ++r) { const int m = m0 + r * NGW < m_hi ? m0 + r * NGW : m_hi - 1; const u32x2* xr = (const u32x2*)(hb + (size_t)m * D) + lane;
; #pragma unroll
;             for (int j = 0; j < 4; ++j) w[r][j] = xr[64 * j]; }
; #pragma unroll
;         for (int r = 0; r < 4; ++r) { const int m = m0 + r * NGW; f32x4 v[4]; float s = 0.f;
; #pragma unroll
;             for (int j = 0; j < 4; ++j) { v[j] = (f32x4){bf_lo(w[r][j].x), bf_hi(w[r][j].x), bf_lo(w[r][j].y), bf_hi(w[r][j].y)}; s += (v[j].x * v[j].x + v[j].y * v[j].y) + (v[j].z * v[j].z + v[j].w * v[j].w); }
;             const float rstd = 1.0f / sqrtf(wave_sum(s) * (1.0f / D) + EPS);
.LBB0_17:
	s_min_i32 s10, s8, s7
	s_ashr_i32 s11, s10, 31
	s_lshl_b64 s[10:11], s[10:11], 11
	v_lshl_add_u64 v[20:21], v[16:17], 0, s[10:11]
	s_add_i32 s10, s8, s1
	s_min_i32 s12, s10, s7
	global_load_dwordx2 v[38:39], v[20:21], off
	global_load_dwordx2 v[40:41], v[20:21], off offset:512
	global_load_dwordx2 v[42:43], v[20:21], off offset:1024
	global_load_dwordx2 v[58:59], v[20:21], off offset:1536
	s_ashr_i32 s13, s12, 31
	s_lshl_b64 s[12:13], s[12:13], 11
	v_lshl_add_u64 v[20:21], v[16:17], 0, s[12:13]
	global_load_dwordx2 v[66:67], v[20:21], off
	global_load_dwordx2 v[62:63], v[20:21], off offset:512
	global_load_dwordx2 v[60:61], v[20:21], off offset:1024
	global_load_dwordx2 v[64:65], v[20:21], off offset:1536
	s_mul_i32 s11, s1, 3
	s_add_i32 s14, s16, s8
	s_add_i32 s12, s11, s8
	s_ashr_i32 s9, s8, 31
	s_min_i32 s18, s14, s7
	s_min_i32 s20, s12, s7
	s_lshl_b64 s[8:9], s[8:9], 12
	s_ashr_i32 s19, s18, 31
	s_ashr_i32 s21, s20, 31
	s_waitcnt lgkmcnt(0)
	v_lshl_add_u64 v[36:37], v[18:19], 0, s[8:9]
	s_lshl_b64 s[8:9], s[18:19], 11
	s_lshl_b64 s[18:19], s[20:21], 11
	v_lshl_add_u64 v[20:21], v[16:17], 0, s[8:9]
	v_lshl_add_u64 v[44:45], v[16:17], 0, s[18:19]
	global_load_dwordx2 v[34:35], v[20:21], off
	global_load_dwordx2 v[32:33], v[20:21], off offset:512
	global_load_dwordx2 v[30:31], v[20:21], off offset:1024
	global_load_dwordx2 v[28:29], v[20:21], off offset:1536
	global_load_dwordx2 v[26:27], v[44:45], off
	global_load_dwordx2 v[24:25], v[44:45], off offset:512
	global_load_dwordx2 v[22:23], v[44:45], off offset:1024
	s_nop 0
	global_load_dwordx2 v[20:21], v[44:45], off offset:1536
	s_mov_b32 s8, 0xf800000
	s_cmp_ge_i32 s10, s0
	s_waitcnt vmcnt(15)
	v_and_b32_e32 v77, 0xffff0000, v38
	v_and_b32_e32 v57, 0xffff0000, v39
	v_lshlrev_b32_e32 v76, 16, v38
	v_lshlrev_b32_e32 v56, 16, v39
	s_waitcnt vmcnt(14)
	v_and_b32_e32 v53, 0xffff0000, v41
	v_and_b32_e32 v52, 0xffff0000, v40
	s_waitcnt vmcnt(13)
	v_and_b32_e32 v49, 0xffff0000, v42
	s_waitcnt vmcnt(12)
	v_lshlrev_b32_e32 v47, 16, v58
	v_and_b32_e32 v45, 0xffff0000, v58
	v_mul_f32_e32 v44, v57, v57
	v_mul_f32_e32 v46, v77, v77
	v_lshlrev_b32_e32 v55, 16, v41
	v_lshlrev_b32_e32 v54, 16, v40
	v_lshlrev_b32_e32 v48, 16, v42
	v_lshlrev_b32_e32 v50, 16, v43
	v_and_b32_e32 v51, 0xffff0000, v43
	v_lshlrev_b32_e32 v42, 16, v59
	v_and_b32_e32 v43, 0xffff0000, v59
	v_pk_mul_f32 v[58:59], v[52:53], v[52:53]
	v_mov_b32_e32 v69, v47
	v_mul_f32_e32 v68, v49, v49
	s_waitcnt vmcnt(11)
	v_lshlrev_b32_e32 v40, 16, v66
	v_and_b32_e32 v41, 0xffff0000, v66
	v_lshlrev_b32_e32 v38, 16, v67
	v_and_b32_e32 v39, 0xffff0000, v67
	v_pk_fma_f32 v[66:67], v[56:57], v[56:57], v[44:45] op_sel_hi:[1,1,0]
	v_pk_fma_f32 v[80:81], v[76:77], v[76:77], v[46:47] op_sel_hi:[1,1,0]
	v_mul_f32_e32 v78, v51, v51
	v_pk_fma_f32 v[58:59], v[54:55], v[54:55], v[58:59]
	v_pk_fma_f32 v[82:83], v[48:49], v[48:49], v[68:69] op_sel_hi:[1,1,0]
	v_mov_b32_e32 v46, v80
	v_mov_b32_e32 v68, v66
	v_mul_f32_e32 v84, v45, v45
	v_mul_f32_e32 v85, v42, v42
	v_mul_f32_e32 v86, v43, v43
	v_pk_fma_f32 v[78:79], v[50:51], v[50:51], v[78:79] op_sel_hi:[1,1,0]
	v_pk_add_f32 v[66:67], v[80:81], v[66:67]
	v_pk_add_f32 v[58:59], v[58:59], v[58:59] op_sel:[0,1] op_sel_hi:[1,0]
	v_pk_mul_f32 v[68:69], v[46:47], v[68:69]
	v_mov_b32_e32 v83, v85
	v_mov_b32_e32 v79, v86
	v_mov_b32_e32 v59, v84
	v_mov_b32_e32 v67, v69
	v_pk_add_f32 v[78:79], v[82:83], v[78:79]
	v_pk_add_f32 v[58:59], v[66:67], v[58:59]
	s_waitcnt vmcnt(9)
	v_lshlrev_b32_e32 v66, 16, v60
	v_pk_add_f32 v[58:59], v[58:59], v[78:79]
	v_mul_f32_e32 v78, v41, v41
	v_add_f32_e32 v44, v58, v59
	ds_bpermute_b32 v46, v70, v44
	v_lshlrev_b32_e32 v58, 16, v62
	v_and_b32_e32 v59, 0xffff0000, v62
	v_lshlrev_b32_e32 v62, 16, v63
	v_and_b32_e32 v63, 0xffff0000, v63
	s_waitcnt lgkmcnt(0)
	v_add_f32_e32 v44, v44, v46
	ds_bpermute_b32 v46, v71, v44
	v_mul_f32_e32 v79, v39, v39
	v_mul_f32_e32 v80, v59, v59
	v_mul_f32_e32 v81, v63, v63
	v_and_b32_e32 v67, 0xffff0000, v60
	s_waitcnt lgkmcnt(0)
	v_add_f32_e32 v44, v44, v46
	ds_bpermute_b32 v46, v72, v44
	v_lshlrev_b32_e32 v60, 16, v61
	v_and_b32_e32 v61, 0xffff0000, v61
	v_fmac_f32_e32 v78, v40, v40
	v_fmac_f32_e32 v79, v38, v38
	s_waitcnt lgkmcnt(0)
	v_add_f32_e32 v44, v44, v46
	ds_bpermute_b32 v46, v73, v44
	v_fmac_f32_e32 v80, v58, v58
	v_fmac_f32_e32 v81, v62, v62
	v_mul_f32_e32 v82, v67, v67
	v_mul_f32_e32 v83, v61, v61
	s_waitcnt lgkmcnt(0)
	v_add_f32_e32 v44, v44, v46
	ds_bpermute_b32 v46, v74, v44
	v_add_f32_e32 v78, v78, v79
	v_add_f32_e32 v79, v80, v81
	v_fmac_f32_e32 v82, v66, v66
	v_fmac_f32_e32 v83, v60, v60
	s_waitcnt lgkmcnt(0)
	v_add_f32_e32 v44, v44, v46
	ds_bpermute_b32 v46, v75, v44
	v_add_f32_e32 v78, v78, v79
	v_add_f32_e32 v80, v82, v83
	v_add_f32_e32 v78, v78, v80
	s_waitcnt vmcnt(8)
	v_lshlrev_b32_e32 v68, 16, v64
	s_waitcnt lgkmcnt(0)
	v_add_f32_e32 v44, v44, v46
	v_fmamk_f32 v44, v44, 0x3a800000, v223
	v_mul_f32_e32 v46, 0x4f800000, v44
	v_cmp_gt_f32_e32 vcc, s8, v44
	v_and_b32_e32 v69, 0xffff0000, v64
	v_lshlrev_b32_e32 v64, 16, v65
	v_cndmask_b32_e32 v44, v44, v46, vcc
	v_sqrt_f32_e32 v46, v44
	v_and_b32_e32 v65, 0xffff0000, v65
	v_add_u32_e32 v79, -1, v46
	v_add_u32_e32 v81, 1, v46
	v_fma_f32 v82, -v79, v46, v44
	v_fma_f32 v83, -v81, v46, v44
	v_cmp_ge_f32_e64 s[8:9], 0, v82
	s_nop 1
	v_cndmask_b32_e64 v46, v46, v79, s[8:9]
	v_cmp_lt_f32_e64 s[8:9], 0, v83
	s_nop 1
	v_cndmask_b32_e64 v46, v46, v81, s[8:9]
	v_mul_f32_e32 v79, 0x37800000, v46
	v_cndmask_b32_e32 v46, v46, v79, vcc
	v_cmp_class_f32_e32 vcc, v44, v224
	s_nop 1
	v_cndmask_b32_e32 v44, v46, v44, vcc
	v_div_scale_f32 v46, s[8:9], v44, v44, 1.0
	v_rcp_f32_e32 v79, v46
	v_div_scale_f32 v80, vcc, 1.0, v44, 1.0
	v_fma_f32 v81, -v46, v79, 1.0
	v_fmac_f32_e32 v79, v81, v79
	v_mul_f32_e32 v81, v80, v79
	v_fma_f32 v82, -v46, v81, v80
	v_fmac_f32_e32 v81, v82, v79
	v_fma_f32 v46, -v46, v81, v80
	v_div_fmas_f32 v46, v46, v79, v81
	v_div_fixup_f32 v46, v46, v44, 1.0
	v_mul_f32_e32 v44, v69, v69
	v_mul_f32_e32 v79, v65, v65
	v_fmac_f32_e32 v44, v68, v68
	v_fmac_f32_e32 v79, v64, v64
	v_add_f32_e32 v44, v44, v79
	v_add_f32_e32 v44, v78, v44
	ds_bpermute_b32 v80, v70, v44
	v_pk_mul_f32 v[76:77], v[46:47], v[76:77] op_sel_hi:[0,1]
	v_pk_mul_f32 v[56:57], v[46:47], v[56:57] op_sel_hi:[0,1]
	v_pk_mul_f32 v[78:79], v[2:3], v[56:57]
	v_pk_mul_f32 v[76:77], v[0:1], v[76:77]
	s_waitcnt lgkmcnt(0)
; __device__ __forceinline__ float bf_lo(unsigned u) { return __uint_as_float(u << 16); }
; __device__ __forceinline__ float bf_hi(unsigned u) { return __uint_as_float(u & 0xffff0000u); }
; __device__ __forceinline__ void final_rows(const bf16_t* hb, const float* g, float* outf, int gw, int NGW, int lane, int m_lo, int m_hi) {
;     ...
;         for (int r = 0; r < 4; ++r) { const int m = m0 + r * NGW; f32x4 v[4]; float s = 0.f;
; #pragma unroll
;             for (int j = 0; j < 4; ++j) { v[j] = (f32x4){bf_lo(w[r][j].x), bf_hi(w[r][j].x), bf_lo(w[r][j].y), bf_hi(w[r][j].y)}; s += (v[j].x * v[j].x + v[j].y * v[j].y) + (v[j].z * v[j].z + v[j].w * v[j].w); }
;             const float rstd = 1.0f / sqrtf(wave_sum(s) * (1.0f / D) + EPS);
;             if (m < m_hi) { f32x4* o = (f32x4*)(outf + (size_t)m * D) + lane;
; #pragma unroll
;                 for (int j = 0; j < 4; ++j) o[64 * j] = v[j] * rstd * gv[j]; } }
	v_add_f32_e32 v44, v44, v80
	global_store_dwordx4 v[36:37], v[76:79], off nt
	ds_bpermute_b32 v76, v71, v44
	v_mov_b32_e32 v56, v54
	v_mov_b32_e32 v57, v52
	v_mov_b32_e32 v52, v55
	v_pk_mul_f32 v[56:57], v[46:47], v[56:57] op_sel_hi:[0,1]
	s_waitcnt lgkmcnt(0)
	v_add_f32_e32 v44, v44, v76
	ds_bpermute_b32 v76, v72, v44
	v_pk_mul_f32 v[52:53], v[46:47], v[52:53] op_sel_hi:[0,1]
	v_pk_mul_f32 v[54:55], v[6:7], v[52:53]
	v_pk_mul_f32 v[52:53], v[4:5], v[56:57]
	global_store_dwordx4 v[36:37], v[52:55], off offset:1024 nt
	s_waitcnt lgkmcnt(0)
	v_add_f32_e32 v44, v44, v76
	ds_bpermute_b32 v52, v73, v44
	v_pk_mul_f32 v[48:49], v[46:47], v[48:49] op_sel_hi:[0,1]
	v_pk_mul_f32 v[50:51], v[46:47], v[50:51] op_sel_hi:[0,1]
	v_pk_mul_f32 v[50:51], v[10:11], v[50:51]
	v_pk_mul_f32 v[48:49], v[8:9], v[48:49]
	s_waitcnt lgkmcnt(0)
	v_add_f32_e32 v52, v44, v52
	ds_bpermute_b32 v53, v74, v52
	v_mov_b32_e32 v44, v47
	v_pk_mul_f32 v[44:45], v[44:45], v[46:47] op_sel_hi:[1,0]
	v_pk_mul_f32 v[46:47], v[42:43], v[46:47] op_sel_hi:[1,0]
	v_pk_mul_f32 v[44:45], v[12:13], v[44:45]
	s_waitcnt lgkmcnt(0)
	v_add_f32_e32 v42, v52, v53
	ds_bpermute_b32 v43, v75, v42
	v_pk_mul_f32 v[46:47], v[14:15], v[46:47]
	global_store_dwordx4 v[36:37], v[48:51], off offset:2048 nt
	global_store_dwordx4 v[36:37], v[44:47], off offset:3072 nt
	s_cbranch_scc1 .LBB0_19
	s_waitcnt lgkmcnt(0)
	v_add_f32_e32 v36, v42, v43
	v_fmamk_f32 v36, v36, 0x3a800000, v223
	s_mov_b32 s8, 0xf800000
	v_mul_f32_e32 v37, 0x4f800000, v36
	v_cmp_gt_f32_e32 vcc, s8, v36
	s_ashr_i32 s11, s10, 31
	s_nop 0
	v_cndmask_b32_e32 v36, v36, v37, vcc
	v_sqrt_f32_e32 v37, v36
	s_nop 0
	v_add_u32_e32 v42, -1, v37
	v_fma_f32 v44, -v42, v37, v36
	v_add_u32_e32 v43, 1, v37
	v_cmp_ge_f32_e64 s[8:9], 0, v44
	s_nop 1
	v_cndmask_b32_e64 v42, v37, v42, s[8:9]
	v_fma_f32 v37, -v43, v37, v36
	v_cmp_lt_f32_e64 s[8:9], 0, v37
	s_nop 1
	v_cndmask_b32_e64 v37, v42, v43, s[8:9]
	v_mul_f32_e32 v42, 0x37800000, v37
	v_cndmask_b32_e32 v37, v37, v42, vcc
	v_cmp_class_f32_e32 vcc, v36, v224
	s_nop 1
	v_cndmask_b32_e32 v36, v37, v36, vcc
	v_div_scale_f32 v37, s[8:9], v36, v36, 1.0
	v_rcp_f32_e32 v42, v37
	s_lshl_b64 s[8:9], s[10:11], 12
	v_fma_f32 v43, -v37, v42, 1.0
	v_fmac_f32_e32 v42, v43, v42
	v_div_scale_f32 v43, vcc, 1.0, v36, 1.0
	v_mul_f32_e32 v44, v43, v42
	v_fma_f32 v45, -v37, v44, v43
	v_fmac_f32_e32 v44, v45, v42
	v_fma_f32 v37, -v37, v44, v43
	v_div_fmas_f32 v37, v37, v42, v44
	v_div_fixup_f32 v42, v37, v36, 1.0
	v_pk_mul_f32 v[36:37], v[40:41], v[42:43] op_sel_hi:[1,0]
	v_pk_mul_f32 v[38:39], v[38:39], v[42:43] op_sel_hi:[1,0]
	v_lshl_add_u64 v[44:45], v[18:19], 0, s[8:9]
	v_pk_mul_f32 v[38:39], v[2:3], v[38:39]
	v_pk_mul_f32 v[36:37], v[0:1], v[36:37]
	global_store_dwordx4 v[44:45], v[36:39], off nt
	s_nop 1
	v_pk_mul_f32 v[36:37], v[58:59], v[42:43] op_sel_hi:[1,0]
	v_pk_mul_f32 v[38:39], v[62:63], v[42:43] op_sel_hi:[1,0]
	v_pk_mul_f32 v[36:37], v[4:5], v[36:37]
	v_pk_mul_f32 v[38:39], v[6:7], v[38:39]
	global_store_dwordx4 v[44:45], v[36:39], off offset:1024 nt
	s_nop 1
	v_pk_mul_f32 v[36:37], v[66:67], v[42:43] op_sel_hi:[1,0]
	v_pk_mul_f32 v[38:39], v[60:61], v[42:43] op_sel_hi:[1,0]
	v_pk_mul_f32 v[36:37], v[8:9], v[36:37]
	v_pk_mul_f32 v[38:39], v[10:11], v[38:39]
	global_store_dwordx4 v[44:45], v[36:39], off offset:2048 nt
	s_nop 1
	v_pk_mul_f32 v[36:37], v[68:69], v[42:43] op_sel_hi:[1,0]
	v_pk_mul_f32 v[38:39], v[64:65], v[42:43] op_sel_hi:[1,0]
	v_pk_mul_f32 v[36:37], v[12:13], v[36:37]
	v_pk_mul_f32 v[38:39], v[14:15], v[38:39]
	global_store_dwordx4 v[44:45], v[36:39], off offset:3072 nt
.LBB0_19:
	s_waitcnt vmcnt(11) lgkmcnt(0)
	v_and_b32_e32 v43, 0xffff0000, v34
	v_and_b32_e32 v41, 0xffff0000, v35
	s_waitcnt vmcnt(10)
	v_and_b32_e32 v39, 0xffff0000, v32
	v_and_b32_e32 v37, 0xffff0000, v33
	v_lshlrev_b32_e32 v42, 16, v34
	v_lshlrev_b32_e32 v40, 16, v35
	v_mul_f32_e32 v34, v43, v43
	v_mul_f32_e32 v35, v41, v41
	v_lshlrev_b32_e32 v38, 16, v32
	v_lshlrev_b32_e32 v36, 16, v33
	v_mul_f32_e32 v32, v39, v39
	v_mul_f32_e32 v33, v37, v37
	v_fmac_f32_e32 v34, v42, v42
	v_fmac_f32_e32 v35, v40, v40
	v_fmac_f32_e32 v32, v38, v38
	v_fmac_f32_e32 v33, v36, v36
	v_add_f32_e32 v34, v34, v35
	v_add_f32_e32 v32, v32, v33
	s_waitcnt vmcnt(9)
	v_and_b32_e32 v35, 0xffff0000, v30
	v_and_b32_e32 v33, 0xffff0000, v31
	v_add_f32_e32 v44, v34, v32
	v_lshlrev_b32_e32 v34, 16, v30
	v_lshlrev_b32_e32 v32, 16, v31
	v_mul_f32_e32 v30, v35, v35
	v_mul_f32_e32 v31, v33, v33
	v_fmac_f32_e32 v30, v34, v34
	v_fmac_f32_e32 v31, v32, v32
	v_add_f32_e32 v30, v30, v31
	v_add_f32_e32 v44, v44, v30
	s_waitcnt vmcnt(8)
	v_lshlrev_b32_e32 v30, 16, v28
	v_and_b32_e32 v31, 0xffff0000, v28
	v_lshlrev_b32_e32 v28, 16, v29
	v_and_b32_e32 v29, 0xffff0000, v29
	v_mul_f32_e32 v45, v31, v31
	v_mul_f32_e32 v46, v29, v29
	v_fmac_f32_e32 v45, v30, v30
	v_fmac_f32_e32 v46, v28, v28
	v_add_f32_e32 v45, v45, v46
	v_add_f32_e32 v44, v44, v45
	ds_bpermute_b32 v45, v70, v44
	s_cmp_ge_i32 s14, s0
	s_waitcnt lgkmcnt(0)
	v_add_f32_e32 v44, v44, v45
	ds_bpermute_b32 v45, v71, v44
	s_waitcnt lgkmcnt(0)
	v_add_f32_e32 v44, v44, v45
	ds_bpermute_b32 v45, v72, v44
	s_waitcnt lgkmcnt(0)
	v_add_f32_e32 v44, v44, v45
	ds_bpermute_b32 v45, v73, v44
	s_waitcnt lgkmcnt(0)
	v_add_f32_e32 v44, v44, v45
	ds_bpermute_b32 v45, v74, v44
	s_waitcnt lgkmcnt(0)
	v_add_f32_e32 v44, v44, v45
	ds_bpermute_b32 v45, v75, v44
	s_cbranch_scc1 .LBB0_21
; __device__ __forceinline__ float bf_lo(unsigned u) { return __uint_as_float(u << 16); }
; __device__ __forceinline__ float bf_hi(unsigned u) { return __uint_as_float(u & 0xffff0000u); }
; __device__ __forceinline__ void final_rows(const bf16_t* hb, const float* g, float* outf, int gw, int NGW, int lane, int m_lo, int m_hi) {
;     ...
;         for (int r = 0; r < 4; ++r) { const int m = m0 + r * NGW; f32x4 v[4]; float s = 0.f;
; #pragma unroll
;             for (int j = 0; j < 4; ++j) { v[j] = (f32x4){bf_lo(w[r][j].x), bf_hi(w[r][j].x), bf_lo(w[r][j].y), bf_hi(w[r][j].y)}; s += (v[j].x * v[j].x + v[j].y * v[j].y) + (v[j].z * v[j].z + v[j].w * v[j].w); }
;             const float rstd = 1.0f / sqrtf(wave_sum(s) * (1.0f / D) + EPS);
;             if (m < m_hi) { f32x4* o = (f32x4*)(outf + (size_t)m * D) + lane;
; #pragma unroll
;                 for (int j = 0; j < 4; ++j) o[64 * j] = v[j] * rstd * gv[j]; } }
	s_waitcnt lgkmcnt(0)
	v_add_f32_e32 v44, v44, v45
	v_fmamk_f32 v44, v44, 0x3a800000, v223
	s_mov_b32 s8, 0xf800000
	v_mul_f32_e32 v45, 0x4f800000, v44
	v_cmp_gt_f32_e32 vcc, s8, v44
	s_ashr_i32 s15, s14, 31
	s_nop 0
	v_cndmask_b32_e32 v44, v44, v45, vcc
	v_sqrt_f32_e32 v45, v44
	s_nop 0
	v_add_u32_e32 v46, -1, v45
	v_fma_f32 v48, -v46, v45, v44
	v_add_u32_e32 v47, 1, v45
	v_cmp_ge_f32_e64 s[8:9], 0, v48
	s_nop 1
	v_cndmask_b32_e64 v46, v45, v46, s[8:9]
	v_fma_f32 v45, -v47, v45, v44
	v_cmp_lt_f32_e64 s[8:9], 0, v45
	s_nop 1
	v_cndmask_b32_e64 v45, v46, v47, s[8:9]
	v_mul_f32_e32 v46, 0x37800000, v45
	v_cndmask_b32_e32 v45, v45, v46, vcc
	v_cmp_class_f32_e32 vcc, v44, v224
	s_nop 1
	v_cndmask_b32_e32 v44, v45, v44, vcc
	v_div_scale_f32 v45, s[8:9], v44, v44, 1.0
	v_rcp_f32_e32 v46, v45
	s_lshl_b64 s[8:9], s[14:15], 12
	v_fma_f32 v47, -v45, v46, 1.0
	v_fmac_f32_e32 v46, v47, v46
	v_div_scale_f32 v47, vcc, 1.0, v44, 1.0
	v_mul_f32_e32 v48, v47, v46
	v_fma_f32 v49, -v45, v48, v47
	v_fmac_f32_e32 v48, v49, v46
	v_fma_f32 v45, -v45, v48, v47
	v_div_fmas_f32 v45, v45, v46, v48
	v_div_fixup_f32 v44, v45, v44, 1.0
	v_pk_mul_f32 v[48:49], v[42:43], v[44:45] op_sel_hi:[1,0]
	v_pk_mul_f32 v[40:41], v[40:41], v[44:45] op_sel_hi:[1,0]
	v_lshl_add_u64 v[46:47], v[18:19], 0, s[8:9]
	v_pk_mul_f32 v[42:43], v[2:3], v[40:41]
	v_pk_mul_f32 v[40:41], v[0:1], v[48:49]
	global_store_dwordx4 v[46:47], v[40:43], off nt
	v_pk_mul_f32 v[36:37], v[36:37], v[44:45] op_sel_hi:[1,0]
	v_pk_mul_f32 v[32:33], v[32:33], v[44:45] op_sel_hi:[1,0]
	v_pk_mul_f32 v[40:41], v[38:39], v[44:45] op_sel_hi:[1,0]
	v_pk_mul_f32 v[38:39], v[6:7], v[36:37]
	v_pk_mul_f32 v[36:37], v[4:5], v[40:41]
	global_store_dwordx4 v[46:47], v[36:39], off offset:1024 nt
	v_pk_mul_f32 v[28:29], v[28:29], v[44:45] op_sel_hi:[1,0]
	s_nop 0
	v_pk_mul_f32 v[36:37], v[34:35], v[44:45] op_sel_hi:[1,0]
	v_pk_mul_f32 v[34:35], v[10:11], v[32:33]
	v_pk_mul_f32 v[32:33], v[8:9], v[36:37]
	global_store_dwordx4 v[46:47], v[32:35], off offset:2048 nt
	s_nop 1
	v_pk_mul_f32 v[32:33], v[30:31], v[44:45] op_sel_hi:[1,0]
	v_pk_mul_f32 v[30:31], v[14:15], v[28:29]
	v_pk_mul_f32 v[28:29], v[12:13], v[32:33]
	global_store_dwordx4 v[46:47], v[28:31], off offset:3072 nt
.LBB0_21:
	s_waitcnt vmcnt(7)
	v_and_b32_e32 v35, 0xffff0000, v26
	v_and_b32_e32 v33, 0xffff0000, v27
	s_waitcnt vmcnt(6)
	v_and_b32_e32 v31, 0xffff0000, v24
	v_and_b32_e32 v29, 0xffff0000, v25
	v_lshlrev_b32_e32 v34, 16, v26
	v_lshlrev_b32_e32 v32, 16, v27
	v_mul_f32_e32 v26, v35, v35
	v_mul_f32_e32 v27, v33, v33
	v_lshlrev_b32_e32 v30, 16, v24
	v_lshlrev_b32_e32 v28, 16, v25
	v_mul_f32_e32 v24, v31, v31
	v_mul_f32_e32 v25, v29, v29
	v_fmac_f32_e32 v26, v34, v34
	v_fmac_f32_e32 v27, v32, v32
	v_fmac_f32_e32 v24, v30, v30
	v_fmac_f32_e32 v25, v28, v28
	v_add_f32_e32 v26, v26, v27
	v_add_f32_e32 v24, v24, v25
	s_waitcnt vmcnt(5)
	v_and_b32_e32 v27, 0xffff0000, v22
	v_and_b32_e32 v25, 0xffff0000, v23
	v_add_f32_e32 v36, v26, v24
	v_lshlrev_b32_e32 v26, 16, v22
	v_lshlrev_b32_e32 v24, 16, v23
	v_mul_f32_e32 v22, v27, v27
	v_mul_f32_e32 v23, v25, v25
	v_fmac_f32_e32 v22, v26, v26
	v_fmac_f32_e32 v23, v24, v24
	v_add_f32_e32 v22, v22, v23
	v_add_f32_e32 v36, v36, v22
	s_waitcnt vmcnt(4)
	v_lshlrev_b32_e32 v22, 16, v20
	v_and_b32_e32 v23, 0xffff0000, v20
	v_lshlrev_b32_e32 v20, 16, v21
	v_and_b32_e32 v21, 0xffff0000, v21
	v_mul_f32_e32 v37, v23, v23
	v_mul_f32_e32 v38, v21, v21
	v_fmac_f32_e32 v37, v22, v22
	v_fmac_f32_e32 v38, v20, v20
	v_add_f32_e32 v37, v37, v38
	v_add_f32_e32 v36, v36, v37
	ds_bpermute_b32 v37, v70, v36
	s_cmp_ge_i32 s12, s0
	s_waitcnt lgkmcnt(0)
	v_add_f32_e32 v36, v36, v37
	ds_bpermute_b32 v37, v71, v36
	s_waitcnt lgkmcnt(0)
	v_add_f32_e32 v36, v36, v37
	ds_bpermute_b32 v37, v72, v36
	s_waitcnt lgkmcnt(0)
	v_add_f32_e32 v36, v36, v37
	ds_bpermute_b32 v37, v73, v36
	s_waitcnt lgkmcnt(0)
	v_add_f32_e32 v36, v36, v37
	ds_bpermute_b32 v37, v74, v36
	s_waitcnt lgkmcnt(0)
	v_add_f32_e32 v36, v36, v37
	ds_bpermute_b32 v37, v75, v36
	s_cbranch_scc1 .LBB0_16
	s_waitcnt lgkmcnt(0)
	v_add_f32_e32 v36, v36, v37
	v_fmamk_f32 v36, v36, 0x3a800000, v223
	s_mov_b32 s8, 0xf800000
	v_mul_f32_e32 v37, 0x4f800000, v36
	v_cmp_gt_f32_e32 vcc, s8, v36
	s_ashr_i32 s13, s12, 31
	s_nop 0
	v_cndmask_b32_e32 v36, v36, v37, vcc
	v_sqrt_f32_e32 v37, v36
	s_nop 0
	v_add_u32_e32 v38, -1, v37
	v_fma_f32 v40, -v38, v37, v36
	v_add_u32_e32 v39, 1, v37
	v_cmp_ge_f32_e64 s[8:9], 0, v40
	s_nop 1
	v_cndmask_b32_e64 v38, v37, v38, s[8:9]
	v_fma_f32 v37, -v39, v37, v36
	v_cmp_lt_f32_e64 s[8:9], 0, v37
	s_nop 1
	v_cndmask_b32_e64 v37, v38, v39, s[8:9]
	v_mul_f32_e32 v38, 0x37800000, v37
	v_cndmask_b32_e32 v37, v37, v38, vcc
	v_cmp_class_f32_e32 vcc, v36, v224
	s_nop 1
	v_cndmask_b32_e32 v36, v37, v36, vcc
	v_div_scale_f32 v37, s[8:9], v36, v36, 1.0
	v_rcp_f32_e32 v38, v37
	s_lshl_b64 s[8:9], s[12:13], 12
	v_fma_f32 v39, -v37, v38, 1.0
	v_fmac_f32_e32 v38, v39, v38
	v_div_scale_f32 v39, vcc, 1.0, v36, 1.0
	v_mul_f32_e32 v40, v39, v38
	v_fma_f32 v41, -v37, v40, v39
	v_fmac_f32_e32 v40, v41, v38
	v_fma_f32 v37, -v37, v40, v39
	v_div_fmas_f32 v37, v37, v38, v40
	v_div_fixup_f32 v36, v37, v36, 1.0
	v_pk_mul_f32 v[40:41], v[34:35], v[36:37] op_sel_hi:[1,0]
	v_pk_mul_f32 v[32:33], v[32:33], v[36:37] op_sel_hi:[1,0]
	v_lshl_add_u64 v[38:39], v[18:19], 0, s[8:9]
	v_pk_mul_f32 v[34:35], v[2:3], v[32:33]
	v_pk_mul_f32 v[32:33], v[0:1], v[40:41]
	global_store_dwordx4 v[38:39], v[32:35], off nt
	v_pk_mul_f32 v[28:29], v[28:29], v[36:37] op_sel_hi:[1,0]
	v_pk_mul_f32 v[24:25], v[24:25], v[36:37] op_sel_hi:[1,0]
	v_pk_mul_f32 v[32:33], v[30:31], v[36:37] op_sel_hi:[1,0]
	v_pk_mul_f32 v[30:31], v[6:7], v[28:29]
	v_pk_mul_f32 v[28:29], v[4:5], v[32:33]
	global_store_dwordx4 v[38:39], v[28:31], off offset:1024 nt
	v_pk_mul_f32 v[20:21], v[20:21], v[36:37] op_sel_hi:[1,0]
	s_nop 0
	v_pk_mul_f32 v[28:29], v[26:27], v[36:37] op_sel_hi:[1,0]
	v_pk_mul_f32 v[26:27], v[10:11], v[24:25]
	v_pk_mul_f32 v[24:25], v[8:9], v[28:29]
	global_store_dwordx4 v[38:39], v[24:27], off offset:2048 nt
	s_nop 1
	v_pk_mul_f32 v[24:25], v[22:23], v[36:37] op_sel_hi:[1,0]
	v_pk_mul_f32 v[22:23], v[14:15], v[20:21]
	v_pk_mul_f32 v[20:21], v[12:13], v[24:25]
	global_store_dwordx4 v[38:39], v[20:23], off offset:3072 nt
	s_branch .LBB0_16
